# ssm pass2 output: 4x4 quad transpose with DPP -> one dwordx2 store per lane per group instead of 4 short stores
# speedup vs baseline: 1.0091x; 1.0056x over previous
; __device__ __forceinline__ void ssm_pass2(LAS unsigned char* lds, const bf16_t* US, const float* SST, bf16_t* YB, const float* ABAR, const bf16_t* BBH, const bf16_t* BBL, const bf16_t* CMH, const bf16_t* CML, const float* dco, int gw, int NGW, int lane, int wave) {
;     ...
;         SsmOps S; ssm_ops_load(S, ABAR, BBH, BBL, g, lane);
;         bf16x8 ch[4];
; #pragma unroll
;         for (int ks = 0; ks < 4; ++ks) { const size_t o = (size_t)(g * 16 + fr) * 128 + ks * 32 + fq * 8; ch[ks] = *(const bf16x8*)(CMH + o); }
;         const float dh = dco[g * 16 + fr];
;         float pr = S.ar, pi = S.ai;
; #pragma unroll
;         for (int s = 0; s < 8; ++s) { const float nr = pr * pr - pi * pi, ni = 2.f * pr * pi; pr = nr; pi = ni; }
;         float xr = 0.f, xi = 0.f;
;         { float sr[7], sm[7];
; #pragma unroll
;           for (int cc = 0; cc < 7; ++cc) { const float* si = SST + ((size_t)bg * 8 + (cc < c ? cc : 0)) * 128; sr[cc] = si[lane]; sm[cc] = si[64 + lane]; }
; #pragma unroll
;           for (int cc = 0; cc < 7; ++cc) if (cc < c) { const float nr = pr * xr - pi * xi + sr[cc], ni = pr * xi + pi * xr + sm[cc]; xr = nr; xi = ni; } }
;         const int tokc = b * SEQ + c * 256;
;         bf16x8 uh; ssm_u_load(uh, US, tokc, g, lane);
;         for (int grp = 0; grp < 16; ++grp) { const int tok = tokc + grp * 16;
;             ssm_bu_tile(S, uh, tile, lane);
;             if (grp < 15) ssm_u_load(uh, US, tok + 16, g, lane);
.LBB0_549:
	s_and_b32 s21, s68, 0xfffff800
	v_or_b32_e32 v125, s21, v120
	v_or_b32_e32 v126, s21, v121
	s_lshl_b32 s21, s70, 3
	v_mul_f32_e32 v48, v66, v52
	s_and_b32 s21, s21, 0xfffff800
	v_fma_f32 v48, v65, v53, -v48
	s_or_b32 s59, s21, s3
	v_add_f32_e32 v68, v50, v48
	v_or_b32_e32 v48, s59, v114
	v_ashrrev_i32_e32 v49, 31, v48
	v_lshlrev_b64 v[48:49], 10, v[48:49]
	v_lshl_add_u64 v[48:49], s[46:47], 0, v[48:49]
	s_lshl_b32 s20, s20, 1
	s_mov_b32 s21, s57
	v_lshl_add_u64 v[48:49], v[48:49], 0, s[20:21]
	v_lshl_add_u64 v[48:49], v[48:49], 0, v[80:81]
	global_load_dwordx4 v[48:51], v[48:49], off
	v_mul_f32_e32 v67, v66, v53
	v_fmac_f32_e32 v67, v65, v52
	v_add_f32_e32 v64, v64, v67
	v_cndmask_b32_e64 v52, v52, v64, s[8:9]
	v_cndmask_b32_e64 v53, v53, v68, s[8:9]
	v_mul_f32_e32 v64, v66, v53
	v_mul_f32_e32 v67, v66, v52
	v_fmac_f32_e32 v64, v65, v52
	v_fma_f32 v67, v65, v53, -v67
	v_add_f32_e32 v62, v62, v67
	v_add_f32_e32 v63, v63, v64
	v_cndmask_b32_e64 v52, v52, v63, s[10:11]
	v_cndmask_b32_e64 v53, v53, v62, s[10:11]
	v_mul_f32_e32 v62, v66, v53
	v_mul_f32_e32 v63, v66, v52
	v_fmac_f32_e32 v62, v65, v52
	v_fma_f32 v63, v65, v53, -v63
	v_add_f32_e32 v60, v60, v63
	v_add_f32_e32 v61, v61, v62
	v_cndmask_b32_e64 v52, v52, v61, s[12:13]
	v_cndmask_b32_e64 v53, v53, v60, s[12:13]
	v_mul_f32_e32 v60, v66, v53
	v_mul_f32_e32 v61, v66, v52
	v_fmac_f32_e32 v60, v65, v52
	v_fma_f32 v61, v65, v53, -v61
	v_add_f32_e32 v56, v56, v61
	v_add_f32_e32 v57, v57, v60
	v_cndmask_b32_e64 v52, v52, v57, s[14:15]
	v_cndmask_b32_e64 v53, v53, v56, s[14:15]
	v_mul_f32_e32 v56, v66, v53
	v_mul_f32_e32 v57, v66, v52
	v_fmac_f32_e32 v56, v65, v52
	v_fma_f32 v57, v65, v53, -v57
	v_add_f32_e32 v57, v58, v57
	v_add_f32_e32 v56, v59, v56
	v_cndmask_b32_e64 v52, v52, v56, s[16:17]
	v_cndmask_b32_e64 v53, v53, v57, s[16:17]
	v_mul_f32_e32 v56, v66, v53
	v_mul_f32_e32 v57, v66, v52
	v_fmac_f32_e32 v56, v65, v52
	v_fma_f32 v57, v65, v53, -v57
	v_add_f32_e32 v54, v54, v57
	v_add_f32_e32 v55, v55, v56
	v_pk_mov_b32 v[94:95], v[90:91], v[90:91] op_sel:[1,0]
	v_cndmask_b32_e64 v76, v52, v55, s[18:19]
	v_cndmask_b32_e64 v100, v53, v54, s[18:19]
	v_cndmask_b32_e64 v19, 0, v19, s[4:5]
	v_cndmask_b32_e64 v18, 0, v18, s[4:5]
	v_cndmask_b32_e64 v17, 0, v17, s[4:5]
	v_cndmask_b32_e64 v16, 0, v16, s[4:5]
	v_cndmask_b32_e64 v23, 0, v23, s[4:5]
	v_cndmask_b32_e64 v22, 0, v22, s[4:5]
	v_cndmask_b32_e64 v21, 0, v21, s[4:5]
	v_cndmask_b32_e64 v20, 0, v20, s[4:5]
	v_cndmask_b32_e64 v27, 0, v27, s[4:5]
	v_cndmask_b32_e64 v26, 0, v26, s[4:5]
	v_cndmask_b32_e64 v25, 0, v25, s[4:5]
	v_cndmask_b32_e64 v24, 0, v24, s[4:5]
	v_cndmask_b32_e64 v31, 0, v31, s[4:5]
	v_cndmask_b32_e64 v30, 0, v30, s[4:5]
	v_cndmask_b32_e64 v29, 0, v29, s[4:5]
	v_cndmask_b32_e64 v28, 0, v28, s[4:5]
	v_cndmask_b32_e64 v35, 0, v35, s[4:5]
	v_cndmask_b32_e64 v34, 0, v34, s[4:5]
	v_cndmask_b32_e64 v33, 0, v33, s[4:5]
	v_cndmask_b32_e64 v32, 0, v32, s[4:5]
	v_cndmask_b32_e64 v39, 0, v39, s[4:5]
	v_cndmask_b32_e64 v38, 0, v38, s[4:5]
	v_cndmask_b32_e64 v37, 0, v37, s[4:5]
	v_cndmask_b32_e64 v36, 0, v36, s[4:5]
	v_cndmask_b32_e64 v43, 0, v43, s[4:5]
	v_cndmask_b32_e64 v42, 0, v42, s[4:5]
	v_cndmask_b32_e64 v41, 0, v41, s[4:5]
	v_cndmask_b32_e64 v40, 0, v40, s[4:5]
	v_cndmask_b32_e64 v47, 0, v47, s[4:5]
	v_cndmask_b32_e64 v46, 0, v46, s[4:5]
	v_cndmask_b32_e64 v45, 0, v45, s[4:5]
	v_cndmask_b32_e64 v44, 0, v44, s[4:5]
	v_lshl_add_u64 v[98:99], v[84:85], 0, s[20:21]
	v_lshl_add_u64 v[96:97], v[86:87], 0, s[20:21]
	v_lshl_add_u64 v[92:93], v[88:89], 0, s[20:21]
	v_readlane_b32 s98, v249, 18
	s_mov_b32 s100, 0x4000
	s_mov_b32 s101, 0
	s_lshl_b32 s99, s20, 7
	s_mul_i32 s98, s98, 0x3a00
	v_lshrrev_b32_e32 v109, 4, v196
	v_mul_u32_u24_e32 v144, 0x50, v114
	v_lshl_add_u32 v144, v109, 4, v144
	v_add_u32_e32 v144, s98, v144
	v_mul_u32_u24_e32 v145, 0x50, v196
	v_add_u32_e32 v145, s98, v145
	v_lshl_add_u32 v146, v196, 2, s98
	v_add_u32_e32 v146, 0x2800, v146
	v_mul_u32_u24_e32 v147, 0x120, v114
	v_lshl_add_u32 v147, v109, 4, v147
	v_add_u32_e32 v147, s98, v147
	v_add_u32_e32 v147, 0x2800, v147
	v_xor_b32_e32 v77, 0x80000000, v91
	v_add_u32_e32 v108, s59, v114
	v_add_u32_e32 v108, 16, v108
	v_lshlrev_b32_e32 v108, 10, v108
	v_mov_b32_e32 v111, 0
	v_mov_b32_e32 v112, v108
	v_mov_b32_e32 v113, v111
	v_lshl_add_u64 v[148:149], v[98:99], 0, v[112:113]
	global_load_dwordx4 v[56:59], v[148:149], off
	v_lshl_add_u64 v[148:149], v[148:149], 0, s[100:101]
	v_lshlrev_b32_e32 v110, 8, v114
	v_lshl_add_u32 v110, v109, 3, v110
	v_add_u32_e32 v110, s99, v110
	global_load_dwordx2 v[230:231], v110, s[54:55] offset:0
	global_load_dwordx2 v[232:233], v110, s[54:55] offset:128
	global_load_dwordx2 v[234:235], v110, s[54:55] offset:32
	global_load_dwordx2 v[236:237], v110, s[54:55] offset:160
	global_load_dwordx2 v[238:239], v110, s[54:55] offset:64
	global_load_dwordx2 v[240:241], v110, s[54:55] offset:192
	global_load_dwordx2 v[242:243], v110, s[54:55] offset:96
	global_load_dwordx2 v[244:245], v110, s[54:55] offset:224
	v_mov_b32_e32 v109, 0
	v_lshrrev_b32_e32 v108, 4, v196
	v_lshl_add_u32 v108, v108, 2, s59
	v_and_b32_e32 v111, 3, v114
	v_add_u32_e32 v108, v108, v111
	v_lshlrev_b32_e32 v108, 10, v108
	v_lshrrev_b32_e32 v111, 2, v114
	v_lshl_add_u32 v108, v111, 3, v108
	v_add_u32_e32 v108, s20, v108
	v_lshl_add_u64 v[150:151], s[0:1], 0, v[108:109]
	s_mov_b32 s99, 0xffff0000
	s_mov_b32 s20, 0
	s_waitcnt vmcnt(0)
; #define LAS __attribute__((address_space(3)))
; __device__ __forceinline__ void ssm_bu_tile(const SsmOps& S, bf16x8 uh, LAS float* tile, int lane) {
;     const int fr = lane & 15, fq = lane >> 4;
;     if (fq >= 2) uh = (bf16x8){0, 0, 0, 0, 0, 0, 0, 0};
; #pragma unroll
;     for (int nb = 0; nb < 8; ++nb) { f32x4 acc = {0.f, 0.f, 0.f, 0.f};
;         acc = __builtin_amdgcn_mfma_f32_16x16x32_bf16(S.bh[nb], uh, acc, 0, 0, 0);
;         *(LAS f32x4*)(tile + fr * TSTR + 16 * nb + 4 * fq) = acc; }
;     asm volatile("s_waitcnt lgkmcnt(0)" ::: "memory");
; __device__ __forceinline__ void ssm_pass2(LAS unsigned char* lds, const bf16_t* US, const float* SST, bf16_t* YB, const float* ABAR, const bf16_t* BBH, const bf16_t* BBL, const bf16_t* CMH, const bf16_t* CML, const float* dco, int gw, int NGW, int lane, int wave) {
;     ...
;             ssm_bu_tile(S, uh, tile, lane);
;             if (grp < 15) ssm_u_load(uh, US, tok + 16, g, lane);
;             float ud[4];
; #pragma unroll
;             for (int i = 0; i < 4; ++i) ud[i] = bf_lo((unsigned)US[(size_t)(tok + 4 * fq + i) * SSMW + g * 16 + fr]);
;             float br[16], bi[16];
; #pragma unroll
;             for (int t = 0; t < 16; ++t) { br[t] = tile[t * TSTR + lane]; bi[t] = tile[t * TSTR + 64 + lane]; }
;             asm volatile("s_waitcnt lgkmcnt(0)" ::: "memory");
; #pragma unroll
;             for (int t = 0; t < 16; ++t) { const float nr = S.ar * xr - S.ai * xi + br[t], ni = S.ar * xi + S.ai * xr + bi[t]; xr = nr; xi = ni; br[t] = xr; bi[t] = xi; }
; #pragma unroll
;             for (int t = 0; t < 16; ++t) { tile[t * TSTR + lane] = br[t]; tile[t * TSTR + 64 + lane] = bi[t]; }
	v_and_b32_e32 v101, 0xffff, v230
	v_lshrrev_b32_e32 v102, 16, v230
	v_and_b32_e32 v103, 0xffff, v231
	v_lshrrev_b32_e32 v104, 16, v231
	v_lshl_or_b32 v214, v232, 16, v101
	v_and_or_b32 v215, v232, s99, v102
	v_lshl_or_b32 v216, v233, 16, v103
	v_and_or_b32 v217, v233, s99, v104
	v_and_b32_e32 v101, 0xffff, v234
	v_lshrrev_b32_e32 v102, 16, v234
	v_and_b32_e32 v103, 0xffff, v235
	v_lshrrev_b32_e32 v104, 16, v235
	v_lshl_or_b32 v218, v236, 16, v101
	v_and_or_b32 v219, v236, s99, v102
	v_lshl_or_b32 v220, v237, 16, v103
	v_and_or_b32 v221, v237, s99, v104
	v_and_b32_e32 v101, 0xffff, v238
	v_lshrrev_b32_e32 v102, 16, v238
	v_and_b32_e32 v103, 0xffff, v239
	v_lshrrev_b32_e32 v104, 16, v239
	v_lshl_or_b32 v222, v240, 16, v101
	v_and_or_b32 v223, v240, s99, v102
	v_lshl_or_b32 v224, v241, 16, v103
	v_and_or_b32 v225, v241, s99, v104
	v_and_b32_e32 v101, 0xffff, v242
	v_lshrrev_b32_e32 v102, 16, v242
	v_and_b32_e32 v103, 0xffff, v243
	v_lshrrev_b32_e32 v104, 16, v243
	v_lshl_or_b32 v226, v244, 16, v101
	v_and_or_b32 v227, v244, s99, v102
	v_lshl_or_b32 v228, v245, 16, v103
	v_and_or_b32 v229, v245, s99, v104
	s_mov_b32 s98, 0xaaaaaaaa
	s_mov_b32 s99, 0xaaaaaaaa
	s_mov_b32 vcc_lo, 0xcccccccc
	s_mov_b32 vcc_hi, 0xcccccccc
	v_cndmask_b32_e64 v55, v51, 0, s[6:7]
	v_cndmask_b32_e64 v54, v50, 0, s[6:7]
	v_cndmask_b32_e64 v53, v49, 0, s[6:7]
	v_cndmask_b32_e64 v52, v48, 0, s[6:7]
	v_mov_b32_e32 v48, v56
	v_mov_b32_e32 v49, v57
	v_mov_b32_e32 v50, v58
	v_mov_b32_e32 v51, v59
	v_mfma_f32_16x16x32_bf16 v[160:163], v[52:55], v[16:19], 0
	v_mfma_f32_16x16x32_bf16 v[164:167], v[52:55], v[20:23], 0
	v_mfma_f32_16x16x32_bf16 v[168:171], v[52:55], v[24:27], 0
	v_mfma_f32_16x16x32_bf16 v[172:175], v[52:55], v[28:31], 0
	v_mfma_f32_16x16x32_bf16 v[176:179], v[52:55], v[32:35], 0
	v_mfma_f32_16x16x32_bf16 v[180:183], v[52:55], v[36:39], 0
	v_mfma_f32_16x16x32_bf16 v[184:187], v[52:55], v[40:43], 0
	v_mfma_f32_16x16x32_bf16 v[188:191], v[52:55], v[44:47], 0
	v_mfma_f32_16x16x32_bf16 v[156:159], v[52:55], v[152:155], 0
	ds_write_b128 v144, v[160:163]
	ds_write_b128 v144, v[164:167] offset:1280
	ds_write_b128 v144, v[168:171] offset:2560
	ds_write_b128 v144, v[172:175] offset:3840
	ds_write_b128 v144, v[176:179] offset:5120
	ds_write_b128 v144, v[180:183] offset:6400
	ds_write_b128 v144, v[184:187] offset:7680
	ds_write_b128 v144, v[188:191] offset:8960
.Lssm2_grp:
	s_waitcnt lgkmcnt(0)
	ds_read_b128 v[0:3], v145
	ds_read_b128 v[60:63], v145 offset:5120
	ds_read_b128 v[4:7], v145 offset:16
	ds_read_b128 v[64:67], v145 offset:5136
	ds_read_b128 v[8:11], v145 offset:32
	ds_read_b128 v[68:71], v145 offset:5152
	ds_read_b128 v[12:15], v145 offset:48
	ds_read_b128 v[72:75], v145 offset:5168
	v_mov_b32_e32 v232, v156
	v_mov_b32_e32 v233, v157
	v_mov_b32_e32 v234, v158
	v_mov_b32_e32 v235, v159
	v_cndmask_b32_e64 v55, v51, 0, s[6:7]
	v_cndmask_b32_e64 v54, v50, 0, s[6:7]
	v_cndmask_b32_e64 v53, v49, 0, s[6:7]
	v_cndmask_b32_e64 v52, v48, 0, s[6:7]
	global_load_dwordx4 v[48:51], v[148:149], off
	v_lshl_add_u64 v[148:149], v[148:149], 0, s[100:101]
	v_mfma_f32_16x16x32_bf16 v[160:163], v[52:55], v[16:19], 0
	v_mfma_f32_16x16x32_bf16 v[164:167], v[52:55], v[20:23], 0
	v_mfma_f32_16x16x32_bf16 v[168:171], v[52:55], v[24:27], 0
	v_mfma_f32_16x16x32_bf16 v[172:175], v[52:55], v[28:31], 0
	v_mfma_f32_16x16x32_bf16 v[176:179], v[52:55], v[32:35], 0
	v_mfma_f32_16x16x32_bf16 v[180:183], v[52:55], v[36:39], 0
	v_mfma_f32_16x16x32_bf16 v[184:187], v[52:55], v[40:43], 0
	v_mfma_f32_16x16x32_bf16 v[188:191], v[52:55], v[44:47], 0
	v_mfma_f32_16x16x32_bf16 v[156:159], v[52:55], v[152:155], 0
	s_waitcnt lgkmcnt(6)
	v_fmac_f32_e32 v0, v90, v100
	v_fmac_f32_e32 v60, v90, v76
	v_fmac_f32_e32 v0, v77, v76
	v_fmac_f32_e32 v60, v91, v100
	v_fmac_f32_e32 v1, v90, v0
	v_fmac_f32_e32 v61, v90, v60
	v_fmac_f32_e32 v1, v77, v60
	v_fmac_f32_e32 v61, v91, v0
	v_cvt_pk_bf16_f32 v128, v0, v60
	ds_write_b32 v146, v128
	v_fmac_f32_e32 v2, v90, v1
	v_fmac_f32_e32 v62, v90, v61
	v_fmac_f32_e32 v2, v77, v61
	v_fmac_f32_e32 v62, v91, v1
	v_cvt_pk_bf16_f32 v129, v1, v61
	ds_write_b32 v146, v129 offset:288
	v_fmac_f32_e32 v3, v90, v2
	v_fmac_f32_e32 v63, v90, v62
	v_fmac_f32_e32 v3, v77, v62
	v_fmac_f32_e32 v63, v91, v2
	v_cvt_pk_bf16_f32 v130, v2, v62
	ds_write_b32 v146, v130 offset:576
	s_waitcnt lgkmcnt(7)
	v_fmac_f32_e32 v4, v90, v3
	v_fmac_f32_e32 v64, v90, v63
	v_fmac_f32_e32 v4, v77, v63
	v_fmac_f32_e32 v64, v91, v3
	v_cvt_pk_bf16_f32 v131, v3, v63
	ds_write_b32 v146, v131 offset:864
	v_fmac_f32_e32 v5, v90, v4
	v_fmac_f32_e32 v65, v90, v64
	v_fmac_f32_e32 v5, v77, v64
	v_fmac_f32_e32 v65, v91, v4
	v_cvt_pk_bf16_f32 v132, v4, v64
	ds_write_b32 v146, v132 offset:1152
	v_fmac_f32_e32 v6, v90, v5
	v_fmac_f32_e32 v66, v90, v65
	v_fmac_f32_e32 v6, v77, v65
	v_fmac_f32_e32 v66, v91, v5
	v_cvt_pk_bf16_f32 v133, v5, v65
	ds_write_b32 v146, v133 offset:1440
	v_fmac_f32_e32 v7, v90, v6
	v_fmac_f32_e32 v67, v90, v66
	v_fmac_f32_e32 v7, v77, v66
	v_fmac_f32_e32 v67, v91, v6
	v_cvt_pk_bf16_f32 v134, v6, v66
	ds_write_b32 v146, v134 offset:1728
	s_waitcnt lgkmcnt(9)
; __device__ __forceinline__ unsigned cvt_pk_bf16(float lo, float hi) { unsigned r; asm volatile("v_cvt_pk_bf16_f32 %0, %1, %2" : "=v"(r) : "v"(lo), "v"(hi)); return r; }
; #define LAS __attribute__((address_space(3)))
; __device__ __forceinline__ float gelu_tanh(float x) { const float z = 0.7978845608028654f * (x + 0.044715f * x * x * x); const float e = __builtin_amdgcn_exp2f(2.f * LOG2E * z); return 0.5f * x * (2.f - 2.f * __builtin_amdgcn_rcpf(1.f + e)); }
; __device__ __forceinline__ void ssm_pass2(LAS unsigned char* lds, const bf16_t* US, const float* SST, bf16_t* YB, const float* ABAR, const bf16_t* BBH, const bf16_t* BBL, const bf16_t* CMH, const bf16_t* CML, const float* dco, int gw, int NGW, int lane, int wave) {
;     ...
;             for (int t = 0; t < 16; ++t) { const float nr = S.ar * xr - S.ai * xi + br[t], ni = S.ar * xi + S.ai * xr + bi[t]; xr = nr; xi = ni; br[t] = xr; bi[t] = xi; }
; #pragma unroll
;             for (int t = 0; t < 16; ++t) { tile[t * TSTR + lane] = br[t]; tile[t * TSTR + 64 + lane] = bi[t]; }
;             asm volatile("s_waitcnt lgkmcnt(0)" ::: "memory");
;             f32x4 acc = {0.f, 0.f, 0.f, 0.f}, acc2 = {0.f, 0.f, 0.f, 0.f};
;             f32x4 xa[4][2];
; #pragma unroll
;             for (int ks = 0; ks < 4; ++ks) { xa[ks][0] = *(const LAS f32x4*)(tile + fr * TSTR + ks * 32 + fq * 8); xa[ks][1] = *(const LAS f32x4*)(tile + fr * TSTR + ks * 32 + fq * 8 + 4); }
; #pragma unroll
;             for (int ks = 0; ks < 4; ++ks) { const f32x4 x0 = xa[ks][0], x1 = xa[ks][1]; u32x4 h;
;                 h.x = cvt_pk_bf16(x0[0], x0[1]); h.y = cvt_pk_bf16(x0[2], x0[3]); h.z = cvt_pk_bf16(x1[0], x1[1]); h.w = cvt_pk_bf16(x1[2], x1[3]);
;                 const bf16x8 xh = __builtin_bit_cast(bf16x8, h);
;                 if (ks & 1) acc2 = __builtin_amdgcn_mfma_f32_16x16x32_bf16(xh, ch[ks], acc2, 0, 0, 0); else acc = __builtin_amdgcn_mfma_f32_16x16x32_bf16(xh, ch[ks], acc, 0, 0, 0); }
;             acc = acc + acc2;
; #pragma unroll
;             for (int i = 0; i < 4; ++i) { const float y = acc[i] + dh * ud[i];
;                 const unsigned w = cvt_pk_bf16(gelu_tanh(y), 0.f); YB[(size_t)(tok + 4 * fq + i) * SSMW + g * 16 + fr] = (bf16_t)(w & 0xffffu); }
;             asm volatile("s_waitcnt lgkmcnt(0)" ::: "memory");
	v_fmac_f32_e32 v8, v90, v7
	v_fmac_f32_e32 v68, v90, v67
	v_fmac_f32_e32 v8, v77, v67
	v_fmac_f32_e32 v68, v91, v7
	v_cvt_pk_bf16_f32 v135, v7, v67
	ds_write_b32 v146, v135 offset:2016
	v_fmac_f32_e32 v9, v90, v8
	v_fmac_f32_e32 v69, v90, v68
	v_fmac_f32_e32 v9, v77, v68
	v_fmac_f32_e32 v69, v91, v8
	v_cvt_pk_bf16_f32 v136, v8, v68
	ds_write_b32 v146, v136 offset:2304
	v_fmac_f32_e32 v10, v90, v9
	v_fmac_f32_e32 v70, v90, v69
	v_fmac_f32_e32 v10, v77, v69
	v_fmac_f32_e32 v70, v91, v9
	v_cvt_pk_bf16_f32 v137, v9, v69
	ds_write_b32 v146, v137 offset:2592
	v_fmac_f32_e32 v11, v90, v10
	v_fmac_f32_e32 v71, v90, v70
	v_fmac_f32_e32 v11, v77, v70
	v_fmac_f32_e32 v71, v91, v10
	v_cvt_pk_bf16_f32 v138, v10, v70
	ds_write_b32 v146, v138 offset:2880
	s_waitcnt lgkmcnt(11)
	v_fmac_f32_e32 v12, v90, v11
	v_fmac_f32_e32 v72, v90, v71
	v_fmac_f32_e32 v12, v77, v71
	v_fmac_f32_e32 v72, v91, v11
	v_cvt_pk_bf16_f32 v139, v11, v71
	ds_write_b32 v146, v139 offset:3168
	v_fmac_f32_e32 v13, v90, v12
	v_fmac_f32_e32 v73, v90, v72
	v_fmac_f32_e32 v13, v77, v72
	v_fmac_f32_e32 v73, v91, v12
	v_cvt_pk_bf16_f32 v140, v12, v72
	ds_write_b32 v146, v140 offset:3456
	v_fmac_f32_e32 v14, v90, v13
	v_fmac_f32_e32 v74, v90, v73
	v_fmac_f32_e32 v14, v77, v73
	v_fmac_f32_e32 v74, v91, v13
	v_cvt_pk_bf16_f32 v141, v13, v73
	ds_write_b32 v146, v141 offset:3744
	v_fmac_f32_e32 v15, v90, v14
	v_fmac_f32_e32 v75, v90, v74
	v_fmac_f32_e32 v15, v77, v74
	v_fmac_f32_e32 v75, v91, v14
	v_cvt_pk_bf16_f32 v142, v14, v74
	ds_write_b32 v146, v142 offset:4032
	v_cvt_pk_bf16_f32 v143, v15, v75
	ds_write_b32 v146, v143 offset:4320
	v_mov_b32_e32 v100, v15
	v_mov_b32_e32 v76, v75
	s_waitcnt lgkmcnt(0)
	ds_read_b128 v[198:201], v147
	ds_read_b128 v[202:205], v147 offset:64
	ds_read_b128 v[206:209], v147 offset:128
	ds_read_b128 v[210:213], v147 offset:192
	ds_write_b128 v144, v[160:163]
	ds_write_b128 v144, v[164:167] offset:1280
	ds_write_b128 v144, v[168:171] offset:2560
	ds_write_b128 v144, v[172:175] offset:3840
	ds_write_b128 v144, v[176:179] offset:5120
	ds_write_b128 v144, v[180:183] offset:6400
	ds_write_b128 v144, v[184:187] offset:7680
	ds_write_b128 v144, v[188:191] offset:8960
	s_waitcnt lgkmcnt(11)
	v_mfma_f32_16x16x32_bf16 v[92:95], v[198:201], v[214:217], 0
	s_waitcnt lgkmcnt(10)
	v_mfma_f32_16x16x32_bf16 v[96:99], v[202:205], v[218:221], 0
	s_waitcnt lgkmcnt(9)
	v_mfma_f32_16x16x32_bf16 v[92:95], v[206:209], v[222:225], v[92:95]
	s_waitcnt lgkmcnt(8)
	v_mfma_f32_16x16x32_bf16 v[96:99], v[210:213], v[226:229], v[96:99]
	s_add_i32 s20, s20, 1
	s_nop 7
	v_pk_add_f32 v[92:93], v[92:93], v[96:97]
	v_fma_f32 v92, v124, v232, v92
	v_mul_f32_e32 v101, 0x3d372713, v92
	v_pk_add_f32 v[94:95], v[94:95], v[98:99]
	v_fmac_f32_e32 v93, v124, v233
	v_mul_f32_e32 v101, v92, v101
	v_fma_f32 v94, v124, v234, v94
	v_mul_f32_e32 v102, 0.5, v92
	v_mul_f32_e32 v103, 0x3d372713, v93
	v_fma_f32 v92, v92, v101, v92
	v_fmac_f32_e32 v95, v124, v235
	v_mul_f32_e32 v105, 0x3d372713, v94
	v_mul_f32_e32 v103, v93, v103
	v_mul_f32_e32 v92, 0x3f4c422a, v92
	v_mul_f32_e32 v104, 0.5, v93
	v_mul_f32_e32 v107, 0x3d372713, v95
	v_mul_f32_e32 v105, v94, v105
	v_fma_f32 v93, v93, v103, v93
	v_mul_f32_e32 v92, 0x4038aa3b, v92
	v_mul_f32_e32 v106, 0.5, v94
	v_mul_f32_e32 v107, v95, v107
	v_fma_f32 v94, v94, v105, v94
	v_mul_f32_e32 v93, 0x3f4c422a, v93
	v_exp_f32_e32 v92, v92
	v_mul_f32_e32 v108, 0.5, v95
	v_fma_f32 v95, v95, v107, v95
	v_mul_f32_e32 v94, 0x3f4c422a, v94
	v_mul_f32_e32 v93, 0x4038aa3b, v93
	v_mul_f32_e32 v95, 0x3f4c422a, v95
	v_mul_f32_e32 v94, 0x4038aa3b, v94
	v_exp_f32_e32 v93, v93
	v_mul_f32_e32 v95, 0x4038aa3b, v95
	v_exp_f32_e32 v94, v94
	v_exp_f32_e32 v95, v95
	v_add_f32_e32 v92, 1.0, v92
	v_rcp_f32_e32 v92, v92
	v_add_f32_e32 v93, 1.0, v93
	v_add_f32_e32 v94, 1.0, v94
	v_rcp_f32_e32 v93, v93
	v_add_f32_e32 v95, 1.0, v95
	v_rcp_f32_e32 v94, v94
	v_rcp_f32_e32 v95, v95
	v_fma_f32 v92, v92, -2.0, 2.0
	v_fma_f32 v93, v93, -2.0, 2.0
	v_fma_f32 v94, v94, -2.0, 2.0
	v_fma_f32 v95, v95, -2.0, 2.0
	v_mul_f32_e32 v92, v102, v92
	v_mul_f32_e32 v93, v104, v93
	v_mul_f32_e32 v94, v106, v94
	v_mul_f32_e32 v95, v108, v95
	v_mov_b32_dpp v101, v93 quad_perm:[1,0,3,2] row_mask:0xf bank_mask:0xf
	v_mov_b32_dpp v102, v92 quad_perm:[1,0,3,2] row_mask:0xf bank_mask:0xf
	v_mov_b32_dpp v103, v95 quad_perm:[1,0,3,2] row_mask:0xf bank_mask:0xf
	v_mov_b32_dpp v104, v94 quad_perm:[1,0,3,2] row_mask:0xf bank_mask:0xf
	v_cndmask_b32_e64 v105, v92, v101, s[98:99]
	v_cndmask_b32_e64 v106, v102, v93, s[98:99]
	v_cndmask_b32_e64 v107, v94, v103, s[98:99]
	v_cndmask_b32_e64 v108, v104, v95, s[98:99]
	v_mov_b32_dpp v102, v105 quad_perm:[2,3,0,1] row_mask:0xf bank_mask:0xf
	v_mov_b32_dpp v104, v106 quad_perm:[2,3,0,1] row_mask:0xf bank_mask:0xf
	v_mov_b32_dpp v101, v107 quad_perm:[2,3,0,1] row_mask:0xf bank_mask:0xf
	v_mov_b32_dpp v103, v108 quad_perm:[2,3,0,1] row_mask:0xf bank_mask:0xf
	v_cndmask_b32_e32 v92, v105, v101, vcc
	v_cndmask_b32_e32 v94, v102, v107, vcc
	v_cndmask_b32_e32 v93, v106, v103, vcc
	v_cndmask_b32_e32 v95, v104, v108, vcc
	v_cvt_pk_bf16_f32 v92, v92, v93
	v_cvt_pk_bf16_f32 v93, v94, v95
	global_store_dwordx2 v[150:151], v[92:93], off
	v_lshl_add_u64 v[150:151], v[150:151], 0, s[100:101]
	s_cmp_eq_u32 s20, 16
	s_waitcnt vmcnt(1)
	s_cbranch_scc0 .Lssm2_grp
	s_add_i32 s70, s70, s33
	s_add_i32 s68, s68, s69
	s_cmpk_gt_i32 s70, 0xfff
	s_cbranch_scc0 .LBB0_547
